# P8 final-output stores: plain instead of nontemporal so the next tile's in-order vmcnt waits are not blocked by slow nt store acks
# speedup vs baseline: 1.0248x; 1.0061x over previous
; #define FOR_AI_M _Pragma("unroll") for (int ai = 0; ai < 2; ++ai) _Pragma("unroll") for (int m = 0; m < 4; ++m)
; #define FOR_BJ_N _Pragma("unroll") for (int bj = 0; bj < 2; ++bj) _Pragma("unroll") for (int n = 0; n < 2; ++n)
;     __device__ __forceinline__ void operator()(EPI_ARGS) const {
;     ...
;         f32x4 gv[2][2];
; #pragma unroll
;         for (int bj = 0; bj < 2; ++bj)
; #pragma unroll
;             for (int n = 0; n < 2; ++n) gv[bj][n] = *(const f32x4*)(gain + u.pn * 256 + bj * 128 + wc * 32 + n * 16 + 4 * fq);
;         FOR_AI_M {
;             const int row = u.pm * 256 + ai * 128 + wr * 64 + m * 16 + fr;
;             const float rs = rsqrtf(__hip_atomic_load(ssq_o + row, __ATOMIC_RELAXED, __HIP_MEMORY_SCOPE_AGENT) * (1.0f / 2048.0f) + EPS);
;             FOR_BJ_N { const int col = u.pn * 256 + bj * 128 + wc * 32 + n * 16 + 4 * fq;
;                 __builtin_nontemporal_store(acc[ai][bj][m][n] * rs * gv[bj][n], (f32x4*)(out + ((size_t)row * 2048 + col))); }
.LBB0_1334:
	s_or_b64 exec, exec, s[8:9]
	s_ashr_i32 s7, s6, 31
	s_lshl_b64 s[6:7], s[6:7], 2
	s_add_u32 s6, s44, s6
	s_addc_u32 s7, s45, s7
	v_ashrrev_i32_e32 v141, 31, v140
	s_barrier
	s_waitcnt lgkmcnt(0)
	v_lshl_add_u64 v[0:1], v[140:141], 2, s[6:7]
	v_lshl_add_u64 v[140:141], v[138:139], 2, s[4:5]
	global_load_dwordx4 v[12:15], v[0:1], off
	global_load_dwordx4 v[8:11], v[0:1], off offset:64
	global_load_dwordx4 v[4:7], v[0:1], off offset:512
	s_nop 0
	global_load_dwordx4 v[0:3], v[0:1], off offset:576
	v_lshlrev_b64 v[192:193], 13, v[138:139]
	global_load_dword v140, v[140:141], off sc1
	v_add_u32_e32 v184, 16, v136
	v_ashrrev_i32_e32 v185, 31, v184
	v_add_u32_e32 v186, 0x80, v136
	v_add_u32_e32 v188, 0x90, v136
	v_ashrrev_i32_e32 v187, 31, v186
	v_ashrrev_i32_e32 v189, 31, v188
	s_mov_b64 s[6:7], -1
	s_waitcnt vmcnt(0)
	v_fmamk_f32 v140, v140, 0x3a000000, v182
	v_cmp_gt_f32_e32 vcc, s47, v140
	v_mul_f32_e32 v141, 0x4b800000, v140
	s_nop 0
	v_cndmask_b32_e32 v140, v140, v141, vcc
	v_rsq_f32_e32 v140, v140
	s_nop 0
	v_mul_f32_e32 v141, 0x45800000, v140
	v_cndmask_b32_e32 v190, v140, v141, vcc
	v_pk_mul_f32 v[124:125], v[124:125], v[190:191] op_sel_hi:[1,0]
	v_pk_mul_f32 v[126:127], v[126:127], v[190:191] op_sel_hi:[1,0]
	v_pk_mul_f32 v[138:139], v[12:13], v[124:125]
	v_pk_mul_f32 v[140:141], v[14:15], v[126:127]
	v_lshl_add_u64 v[126:127], s[86:87], 0, v[192:193]
	v_lshlrev_b64 v[124:125], 2, v[136:137]
	v_lshl_add_u64 v[136:137], v[126:127], 0, v[124:125]
	v_pk_mul_f32 v[120:121], v[120:121], v[190:191] op_sel_hi:[1,0]
	global_store_dwordx4 v[136:137], v[138:141], off
	v_pk_mul_f32 v[122:123], v[122:123], v[190:191] op_sel_hi:[1,0]
	v_pk_mul_f32 v[136:137], v[8:9], v[120:121]
	v_lshlrev_b64 v[120:121], 2, v[184:185]
	v_pk_mul_f32 v[138:139], v[10:11], v[122:123]
	v_lshl_add_u64 v[122:123], v[126:127], 0, v[120:121]
	v_pk_mul_f32 v[116:117], v[116:117], v[190:191] op_sel_hi:[1,0]
	global_store_dwordx4 v[122:123], v[136:139], off
	v_pk_mul_f32 v[118:119], v[118:119], v[190:191] op_sel_hi:[1,0]
	v_pk_mul_f32 v[114:115], v[114:115], v[190:191] op_sel_hi:[1,0]
	v_pk_mul_f32 v[136:137], v[4:5], v[116:117]
	v_lshlrev_b64 v[116:117], 2, v[186:187]
	v_pk_mul_f32 v[138:139], v[6:7], v[118:119]
	v_lshl_add_u64 v[118:119], v[126:127], 0, v[116:117]
	global_store_dwordx4 v[118:119], v[136:139], off
	v_pk_mul_f32 v[118:119], v[142:143], v[190:191] op_sel_hi:[1,0]
	s_nop 0
	v_pk_mul_f32 v[138:139], v[2:3], v[114:115]
	v_lshlrev_b64 v[114:115], 2, v[188:189]
	v_pk_mul_f32 v[136:137], v[0:1], v[118:119]
	v_lshl_add_u64 v[118:119], v[126:127], 0, v[114:115]
	global_store_dwordx4 v[118:119], v[136:139], off
	v_lshl_add_u64 v[118:119], v[112:113], 2, s[4:5]
	global_load_dword v118, v[118:119], off sc1
	v_lshlrev_b64 v[112:113], 13, v[112:113]
	v_lshl_add_u64 v[112:113], s[86:87], 0, v[112:113]
	v_lshl_add_u64 v[122:123], v[112:113], 0, v[124:125]
	s_waitcnt vmcnt(0)
	v_fmamk_f32 v118, v118, 0x3a000000, v182
	v_cmp_gt_f32_e32 vcc, s47, v118
	v_mul_f32_e32 v119, 0x4b800000, v118
	s_nop 0
	v_cndmask_b32_e32 v118, v118, v119, vcc
	v_rsq_f32_e32 v118, v118
	s_nop 0
	v_mul_f32_e32 v119, 0x45800000, v118
	v_cndmask_b32_e32 v118, v118, v119, vcc
	v_pk_mul_f32 v[108:109], v[108:109], v[118:119] op_sel_hi:[1,0]
	v_pk_mul_f32 v[110:111], v[110:111], v[118:119] op_sel_hi:[1,0]
	v_pk_mul_f32 v[108:109], v[12:13], v[108:109]
	v_pk_mul_f32 v[110:111], v[14:15], v[110:111]
	v_pk_mul_f32 v[104:105], v[104:105], v[118:119] op_sel_hi:[1,0]
	v_pk_mul_f32 v[106:107], v[106:107], v[118:119] op_sel_hi:[1,0]
	global_store_dwordx4 v[122:123], v[108:111], off
	v_pk_mul_f32 v[106:107], v[10:11], v[106:107]
	v_pk_mul_f32 v[104:105], v[8:9], v[104:105]
	v_lshl_add_u64 v[108:109], v[112:113], 0, v[120:121]
	v_pk_mul_f32 v[100:101], v[100:101], v[118:119] op_sel_hi:[1,0]
	v_pk_mul_f32 v[102:103], v[102:103], v[118:119] op_sel_hi:[1,0]
	global_store_dwordx4 v[108:109], v[104:107], off
	v_pk_mul_f32 v[102:103], v[6:7], v[102:103]
	v_pk_mul_f32 v[100:101], v[4:5], v[100:101]
	v_lshl_add_u64 v[104:105], v[112:113], 0, v[116:117]
	global_store_dwordx4 v[104:105], v[100:103], off
	v_pk_mul_f32 v[98:99], v[98:99], v[118:119] op_sel_hi:[1,0]
	s_nop 0
	v_pk_mul_f32 v[102:103], v[144:145], v[118:119] op_sel_hi:[1,0]
	v_pk_mul_f32 v[100:101], v[2:3], v[98:99]
	v_pk_mul_f32 v[98:99], v[0:1], v[102:103]
	v_lshl_add_u64 v[102:103], v[112:113], 0, v[114:115]
	global_store_dwordx4 v[102:103], v[98:101], off
	s_nop 1
	v_lshl_add_u64 v[98:99], v[96:97], 2, s[4:5]
	global_load_dword v98, v[98:99], off sc1
	v_lshlrev_b64 v[96:97], 13, v[96:97]
	v_lshl_add_u64 v[96:97], s[86:87], 0, v[96:97]
	v_lshl_add_u64 v[100:101], v[96:97], 0, v[124:125]
	s_waitcnt vmcnt(0)
	v_fmamk_f32 v98, v98, 0x3a000000, v182
	v_cmp_gt_f32_e32 vcc, s47, v98
	v_mul_f32_e32 v99, 0x4b800000, v98
	s_nop 0
	v_cndmask_b32_e32 v98, v98, v99, vcc
	v_rsq_f32_e32 v98, v98
	s_nop 0
	v_mul_f32_e32 v99, 0x45800000, v98
	v_cndmask_b32_e32 v98, v98, v99, vcc
	v_pk_mul_f32 v[92:93], v[92:93], v[98:99] op_sel_hi:[1,0]
	v_pk_mul_f32 v[94:95], v[94:95], v[98:99] op_sel_hi:[1,0]
	v_pk_mul_f32 v[92:93], v[12:13], v[92:93]
	v_pk_mul_f32 v[94:95], v[14:15], v[94:95]
	v_pk_mul_f32 v[88:89], v[88:89], v[98:99] op_sel_hi:[1,0]
	v_pk_mul_f32 v[90:91], v[90:91], v[98:99] op_sel_hi:[1,0]
	global_store_dwordx4 v[100:101], v[92:95], off
	v_pk_mul_f32 v[90:91], v[10:11], v[90:91]
	v_pk_mul_f32 v[88:89], v[8:9], v[88:89]
	v_lshl_add_u64 v[92:93], v[96:97], 0, v[120:121]
	v_pk_mul_f32 v[84:85], v[84:85], v[98:99] op_sel_hi:[1,0]
	v_pk_mul_f32 v[86:87], v[86:87], v[98:99] op_sel_hi:[1,0]
	global_store_dwordx4 v[92:93], v[88:91], off
	v_pk_mul_f32 v[86:87], v[6:7], v[86:87]
	v_pk_mul_f32 v[84:85], v[4:5], v[84:85]
	v_lshl_add_u64 v[88:89], v[96:97], 0, v[116:117]
	global_store_dwordx4 v[88:89], v[84:87], off
	v_pk_mul_f32 v[82:83], v[82:83], v[98:99] op_sel_hi:[1,0]
	s_nop 0
	v_pk_mul_f32 v[86:87], v[146:147], v[98:99] op_sel_hi:[1,0]
	v_pk_mul_f32 v[84:85], v[2:3], v[82:83]
	v_pk_mul_f32 v[82:83], v[0:1], v[86:87]
	v_lshl_add_u64 v[86:87], v[96:97], 0, v[114:115]
	global_store_dwordx4 v[86:87], v[82:85], off
	s_nop 1
	v_lshl_add_u64 v[82:83], v[80:81], 2, s[4:5]
	global_load_dword v82, v[82:83], off sc1
	v_lshlrev_b64 v[80:81], 13, v[80:81]
	v_lshl_add_u64 v[80:81], s[86:87], 0, v[80:81]
	v_lshl_add_u64 v[84:85], v[80:81], 0, v[124:125]
	s_waitcnt vmcnt(0)
; #define FOR_AI_M _Pragma("unroll") for (int ai = 0; ai < 2; ++ai) _Pragma("unroll") for (int m = 0; m < 4; ++m)
; #define FOR_BJ_N _Pragma("unroll") for (int bj = 0; bj < 2; ++bj) _Pragma("unroll") for (int n = 0; n < 2; ++n)
;     __device__ __forceinline__ void operator()(EPI_ARGS) const {
;     ...
;         FOR_AI_M {
;             const int row = u.pm * 256 + ai * 128 + wr * 64 + m * 16 + fr;
;             const float rs = rsqrtf(__hip_atomic_load(ssq_o + row, __ATOMIC_RELAXED, __HIP_MEMORY_SCOPE_AGENT) * (1.0f / 2048.0f) + EPS);
;             FOR_BJ_N { const int col = u.pn * 256 + bj * 128 + wc * 32 + n * 16 + 4 * fq;
;                 __builtin_nontemporal_store(acc[ai][bj][m][n] * rs * gv[bj][n], (f32x4*)(out + ((size_t)row * 2048 + col))); }
	v_fmamk_f32 v82, v82, 0x3a000000, v182
	v_cmp_gt_f32_e32 vcc, s47, v82
	v_mul_f32_e32 v83, 0x4b800000, v82
	s_nop 0
	v_cndmask_b32_e32 v82, v82, v83, vcc
	v_rsq_f32_e32 v82, v82
	s_nop 0
	v_mul_f32_e32 v83, 0x45800000, v82
	v_cndmask_b32_e32 v82, v82, v83, vcc
	v_pk_mul_f32 v[76:77], v[76:77], v[82:83] op_sel_hi:[1,0]
	v_pk_mul_f32 v[78:79], v[78:79], v[82:83] op_sel_hi:[1,0]
	v_pk_mul_f32 v[76:77], v[12:13], v[76:77]
	v_pk_mul_f32 v[78:79], v[14:15], v[78:79]
	v_pk_mul_f32 v[72:73], v[72:73], v[82:83] op_sel_hi:[1,0]
	v_pk_mul_f32 v[74:75], v[74:75], v[82:83] op_sel_hi:[1,0]
	global_store_dwordx4 v[84:85], v[76:79], off
	v_pk_mul_f32 v[74:75], v[10:11], v[74:75]
	v_pk_mul_f32 v[72:73], v[8:9], v[72:73]
	v_lshl_add_u64 v[76:77], v[80:81], 0, v[120:121]
	v_pk_mul_f32 v[68:69], v[68:69], v[82:83] op_sel_hi:[1,0]
	v_pk_mul_f32 v[70:71], v[70:71], v[82:83] op_sel_hi:[1,0]
	global_store_dwordx4 v[76:77], v[72:75], off
	v_pk_mul_f32 v[70:71], v[6:7], v[70:71]
	v_pk_mul_f32 v[68:69], v[4:5], v[68:69]
	v_lshl_add_u64 v[72:73], v[80:81], 0, v[116:117]
	global_store_dwordx4 v[72:73], v[68:71], off
	v_pk_mul_f32 v[66:67], v[66:67], v[82:83] op_sel_hi:[1,0]
	s_nop 0
	v_pk_mul_f32 v[70:71], v[148:149], v[82:83] op_sel_hi:[1,0]
	v_pk_mul_f32 v[68:69], v[2:3], v[66:67]
	v_pk_mul_f32 v[66:67], v[0:1], v[70:71]
	v_lshl_add_u64 v[70:71], v[80:81], 0, v[114:115]
	global_store_dwordx4 v[70:71], v[66:69], off
	s_nop 1
	v_lshl_add_u64 v[66:67], v[64:65], 2, s[4:5]
	global_load_dword v66, v[66:67], off sc1
	v_lshlrev_b64 v[64:65], 13, v[64:65]
	v_lshl_add_u64 v[64:65], s[86:87], 0, v[64:65]
	v_lshl_add_u64 v[68:69], v[64:65], 0, v[124:125]
	s_waitcnt vmcnt(0)
	v_fmamk_f32 v66, v66, 0x3a000000, v182
	v_cmp_gt_f32_e32 vcc, s47, v66
	v_mul_f32_e32 v67, 0x4b800000, v66
	s_nop 0
	v_cndmask_b32_e32 v66, v66, v67, vcc
	v_rsq_f32_e32 v66, v66
	s_nop 0
	v_mul_f32_e32 v67, 0x45800000, v66
	v_cndmask_b32_e32 v66, v66, v67, vcc
	v_pk_mul_f32 v[60:61], v[60:61], v[66:67] op_sel_hi:[1,0]
	v_pk_mul_f32 v[62:63], v[62:63], v[66:67] op_sel_hi:[1,0]
	v_pk_mul_f32 v[60:61], v[12:13], v[60:61]
	v_pk_mul_f32 v[62:63], v[14:15], v[62:63]
	v_pk_mul_f32 v[56:57], v[56:57], v[66:67] op_sel_hi:[1,0]
	v_pk_mul_f32 v[58:59], v[58:59], v[66:67] op_sel_hi:[1,0]
	global_store_dwordx4 v[68:69], v[60:63], off
	v_pk_mul_f32 v[58:59], v[10:11], v[58:59]
	v_pk_mul_f32 v[56:57], v[8:9], v[56:57]
	v_lshl_add_u64 v[60:61], v[64:65], 0, v[120:121]
	v_pk_mul_f32 v[52:53], v[52:53], v[66:67] op_sel_hi:[1,0]
	v_pk_mul_f32 v[54:55], v[54:55], v[66:67] op_sel_hi:[1,0]
	global_store_dwordx4 v[60:61], v[56:59], off
	v_pk_mul_f32 v[54:55], v[6:7], v[54:55]
	v_pk_mul_f32 v[52:53], v[4:5], v[52:53]
	v_lshl_add_u64 v[56:57], v[64:65], 0, v[116:117]
	global_store_dwordx4 v[56:57], v[52:55], off
	v_lshl_add_u64 v[56:57], v[64:65], 0, v[114:115]
	s_nop 0
	v_pk_mul_f32 v[52:53], v[154:155], v[66:67] op_sel_hi:[1,0]
	v_pk_mul_f32 v[54:55], v[152:153], v[66:67] op_sel_hi:[1,0]
	v_pk_mul_f32 v[52:53], v[0:1], v[52:53]
	v_pk_mul_f32 v[54:55], v[2:3], v[54:55]
	global_store_dwordx4 v[56:57], v[52:55], off
	s_nop 1
	v_lshl_add_u64 v[52:53], v[48:49], 2, s[4:5]
	global_load_dword v52, v[52:53], off sc1
	v_lshlrev_b64 v[48:49], 13, v[48:49]
	v_lshl_add_u64 v[48:49], s[86:87], 0, v[48:49]
	v_lshl_add_u64 v[54:55], v[48:49], 0, v[124:125]
	s_waitcnt vmcnt(0)
; #define FOR_AI_M _Pragma("unroll") for (int ai = 0; ai < 2; ++ai) _Pragma("unroll") for (int m = 0; m < 4; ++m)
; #define FOR_BJ_N _Pragma("unroll") for (int bj = 0; bj < 2; ++bj) _Pragma("unroll") for (int n = 0; n < 2; ++n)
;     __device__ __forceinline__ void operator()(EPI_ARGS) const {
;     ...
;         FOR_AI_M {
;             const int row = u.pm * 256 + ai * 128 + wr * 64 + m * 16 + fr;
;             const float rs = rsqrtf(__hip_atomic_load(ssq_o + row, __ATOMIC_RELAXED, __HIP_MEMORY_SCOPE_AGENT) * (1.0f / 2048.0f) + EPS);
;             FOR_BJ_N { const int col = u.pn * 256 + bj * 128 + wc * 32 + n * 16 + 4 * fq;
;                 __builtin_nontemporal_store(acc[ai][bj][m][n] * rs * gv[bj][n], (f32x4*)(out + ((size_t)row * 2048 + col))); }
;         }
	v_fmamk_f32 v52, v52, 0x3a000000, v182
	v_cmp_gt_f32_e32 vcc, s47, v52
	v_mul_f32_e32 v53, 0x4b800000, v52
	s_nop 0
	v_cndmask_b32_e32 v52, v52, v53, vcc
	v_rsq_f32_e32 v52, v52
	s_nop 0
	v_mul_f32_e32 v53, 0x45800000, v52
	v_cndmask_b32_e32 v52, v52, v53, vcc
	v_pk_mul_f32 v[44:45], v[44:45], v[52:53] op_sel_hi:[1,0]
	v_pk_mul_f32 v[46:47], v[46:47], v[52:53] op_sel_hi:[1,0]
	v_pk_mul_f32 v[44:45], v[12:13], v[44:45]
	v_pk_mul_f32 v[46:47], v[14:15], v[46:47]
	v_pk_mul_f32 v[40:41], v[40:41], v[52:53] op_sel_hi:[1,0]
	v_pk_mul_f32 v[42:43], v[42:43], v[52:53] op_sel_hi:[1,0]
	global_store_dwordx4 v[54:55], v[44:47], off
	v_pk_mul_f32 v[42:43], v[10:11], v[42:43]
	v_pk_mul_f32 v[40:41], v[8:9], v[40:41]
	v_lshl_add_u64 v[44:45], v[48:49], 0, v[120:121]
	v_pk_mul_f32 v[36:37], v[36:37], v[52:53] op_sel_hi:[1,0]
	v_pk_mul_f32 v[38:39], v[38:39], v[52:53] op_sel_hi:[1,0]
	global_store_dwordx4 v[44:45], v[40:43], off
	v_pk_mul_f32 v[38:39], v[6:7], v[38:39]
	v_pk_mul_f32 v[36:37], v[4:5], v[36:37]
	v_lshl_add_u64 v[40:41], v[48:49], 0, v[116:117]
	global_store_dwordx4 v[40:41], v[36:39], off
	v_lshl_add_u64 v[40:41], v[48:49], 0, v[114:115]
	s_nop 0
	v_pk_mul_f32 v[36:37], v[162:163], v[52:53] op_sel_hi:[1,0]
	v_pk_mul_f32 v[38:39], v[160:161], v[52:53] op_sel_hi:[1,0]
	v_pk_mul_f32 v[36:37], v[0:1], v[36:37]
	v_pk_mul_f32 v[38:39], v[2:3], v[38:39]
	global_store_dwordx4 v[40:41], v[36:39], off
	s_nop 1
	v_lshl_add_u64 v[36:37], v[32:33], 2, s[4:5]
	global_load_dword v36, v[36:37], off sc1
	v_lshlrev_b64 v[32:33], 13, v[32:33]
	v_lshl_add_u64 v[32:33], s[86:87], 0, v[32:33]
	v_lshl_add_u64 v[38:39], v[32:33], 0, v[124:125]
	s_waitcnt vmcnt(0)
	v_fmamk_f32 v36, v36, 0x3a000000, v182
	v_cmp_gt_f32_e32 vcc, s47, v36
	v_mul_f32_e32 v37, 0x4b800000, v36
	s_nop 0
	v_cndmask_b32_e32 v36, v36, v37, vcc
	v_rsq_f32_e32 v36, v36
	s_nop 0
	v_mul_f32_e32 v37, 0x45800000, v36
	v_cndmask_b32_e32 v36, v36, v37, vcc
	v_pk_mul_f32 v[28:29], v[28:29], v[36:37] op_sel_hi:[1,0]
	v_pk_mul_f32 v[30:31], v[30:31], v[36:37] op_sel_hi:[1,0]
	v_pk_mul_f32 v[28:29], v[12:13], v[28:29]
	v_pk_mul_f32 v[30:31], v[14:15], v[30:31]
	v_pk_mul_f32 v[24:25], v[24:25], v[36:37] op_sel_hi:[1,0]
	v_pk_mul_f32 v[26:27], v[26:27], v[36:37] op_sel_hi:[1,0]
	global_store_dwordx4 v[38:39], v[28:31], off
	v_pk_mul_f32 v[26:27], v[10:11], v[26:27]
	v_pk_mul_f32 v[24:25], v[8:9], v[24:25]
	v_lshl_add_u64 v[28:29], v[32:33], 0, v[120:121]
	global_store_dwordx4 v[28:29], v[24:27], off
	v_pk_mul_f32 v[22:23], v[22:23], v[36:37] op_sel_hi:[1,0]
	s_nop 0
	v_pk_mul_f32 v[26:27], v[50:51], v[36:37] op_sel_hi:[1,0]
	v_pk_mul_f32 v[24:25], v[6:7], v[22:23]
	v_pk_mul_f32 v[22:23], v[4:5], v[26:27]
	v_lshl_add_u64 v[26:27], v[32:33], 0, v[116:117]
	global_store_dwordx4 v[26:27], v[22:25], off
	v_lshl_add_u64 v[26:27], v[32:33], 0, v[114:115]
	s_nop 0
	v_pk_mul_f32 v[22:23], v[166:167], v[36:37] op_sel_hi:[1,0]
	v_pk_mul_f32 v[24:25], v[164:165], v[36:37] op_sel_hi:[1,0]
	v_pk_mul_f32 v[22:23], v[0:1], v[22:23]
	v_pk_mul_f32 v[24:25], v[2:3], v[24:25]
	global_store_dwordx4 v[26:27], v[22:25], off
	s_nop 1
	v_lshl_add_u64 v[22:23], v[16:17], 2, s[4:5]
	global_load_dword v22, v[22:23], off sc1
	v_lshlrev_b64 v[16:17], 13, v[16:17]
	v_lshl_add_u64 v[16:17], s[86:87], 0, v[16:17]
	s_waitcnt vmcnt(0)
	v_fmamk_f32 v22, v22, 0x3a000000, v182
	v_cmp_gt_f32_e32 vcc, s47, v22
	v_mul_f32_e32 v23, 0x4b800000, v22
	s_nop 0
	v_cndmask_b32_e32 v22, v22, v23, vcc
	v_rsq_f32_e32 v22, v22
	s_nop 0
	v_mul_f32_e32 v23, 0x45800000, v22
	v_cndmask_b32_e32 v22, v22, v23, vcc
	v_pk_mul_f32 v[20:21], v[20:21], v[22:23] op_sel_hi:[1,0]
	v_pk_mul_f32 v[18:19], v[18:19], v[22:23] op_sel_hi:[1,0]
	v_pk_mul_f32 v[12:13], v[12:13], v[20:21]
	v_pk_mul_f32 v[14:15], v[14:15], v[18:19]
	v_lshl_add_u64 v[18:19], v[16:17], 0, v[124:125]
	global_store_dwordx4 v[18:19], v[12:15], off
	s_andn2_b64 vcc, exec, s[24:25]
	s_nop 0
	v_pk_mul_f32 v[12:13], v[150:151], v[22:23] op_sel_hi:[1,0]
	v_pk_mul_f32 v[14:15], v[34:35], v[22:23] op_sel_hi:[1,0]
	v_pk_mul_f32 v[8:9], v[8:9], v[12:13]
	v_pk_mul_f32 v[10:11], v[10:11], v[14:15]
	v_lshl_add_u64 v[12:13], v[16:17], 0, v[120:121]
	global_store_dwordx4 v[12:13], v[8:11], off
	s_nop 1
	v_pk_mul_f32 v[8:9], v[158:159], v[22:23] op_sel_hi:[1,0]
	v_pk_mul_f32 v[10:11], v[156:157], v[22:23] op_sel_hi:[1,0]
	v_pk_mul_f32 v[4:5], v[4:5], v[8:9]
	v_pk_mul_f32 v[6:7], v[6:7], v[10:11]
	v_lshl_add_u64 v[8:9], v[16:17], 0, v[116:117]
	global_store_dwordx4 v[8:9], v[4:7], off
	s_nop 1
	v_pk_mul_f32 v[4:5], v[176:177], v[22:23] op_sel_hi:[1,0]
	v_pk_mul_f32 v[6:7], v[168:169], v[22:23] op_sel_hi:[1,0]
	v_pk_mul_f32 v[0:1], v[0:1], v[4:5]
	v_pk_mul_f32 v[2:3], v[2:3], v[6:7]
	v_lshl_add_u64 v[4:5], v[16:17], 0, v[114:115]
	global_store_dwordx4 v[4:5], v[0:3], off
	s_cbranch_vccnz .LBB0_1301
	s_andn2_b64 vcc, exec, s[18:19]
	s_cbranch_vccnz .LBB0_1300
	s_barrier
	s_branch .LBB0_1300
